# scan phase: step A LDS-DMA issue also deferred into the o-chain waits
# baseline (speedup 1.0000x reference)
.LBB0_369:
	s_or_b64 exec, exec, s[54:55]
	s_lshl_b64 s[54:55], s[52:53], 8
	v_lshl_add_u64 v[4:5], s[54:55], 0, v[114:115]
	v_lshlrev_b64 v[4:5], 7, v[4:5]
	v_lshl_add_u64 v[244:245], v[138:139], 0, v[4:5]
	s_lshl_b64 s[52:53], s[52:53], 10
	v_lshl_add_u64 v[250:251], v[140:141], 0, s[52:53]
	v_add_u32_e32 v208, v180, v117
	v_add_u32_e32 v212, v180, v119
	ds_read_b128 v[100:103], v208
	ds_read_b128 v[96:99], v212
	v_add_u32_e32 v214, v181, v117
	v_add_u32_e32 v218, v181, v119
	v_add_u32_e32 v216, v180, v113
	ds_read_b128 v[104:107], v214
	ds_read_b128 v[92:95], v218
	ds_read_b128 v[224:227], v216 offset:36864
	s_mov_b32 m0, s67
	s_nop 0
	global_load_lds_dwordx4 v[234:235], off
	s_mov_b32 m0, s79
	s_nop 0
	global_load_lds_dwordx4 v[236:237], off
	s_waitcnt lgkmcnt(0)
	v_cndmask_b32_e64 v223, v99, v103, s[42:43]
	v_cndmask_b32_e64 v222, v98, v102, s[42:43]
	v_cndmask_b32_e64 v221, v97, v101, s[42:43]
	v_cndmask_b32_e64 v220, v96, v100, s[42:43]
	v_add_u32_e32 v215, v181, v113
	ds_read_b128 v[228:231], v215 offset:36864
	v_mfma_f32_16x16x32_bf16 v[220:223], v[220:223], v[224:227], 0
	v_cndmask_b32_e64 v227, v95, v107, s[42:43]
	v_cndmask_b32_e64 v226, v94, v106, s[42:43]
	v_cndmask_b32_e64 v225, v93, v105, s[42:43]
	v_cndmask_b32_e64 v224, v92, v104, s[42:43]
	v_add_u32_e32 v219, v151, v154
	v_add_u32_e32 v213, v151, v155
	s_mov_b32 m0, s80
	s_nop 0
	global_load_lds_dwordx4 v[238:239], off
	s_waitcnt lgkmcnt(0)
	v_mfma_f32_16x16x32_bf16 v[220:223], v[224:227], v[228:231], v[220:223]
	ds_read_b128 v[224:227], v184
	ds_read_b128 v[228:231], v219
	v_add_u32_e32 v217, v151, v156
	s_mov_b32 m0, s81
	s_nop 0
	global_load_lds_dwordx4 v[240:241], off
	s_waitcnt lgkmcnt(0)
	v_mfma_f32_16x16x32_bf16 v[220:223], v[224:227], v[228:231], v[220:223]
	ds_read_b128 v[224:227], v184 offset:64
	ds_read_b128 v[228:231], v213
	v_add_u32_e32 v209, v151, v157
	s_mov_b32 m0, s82
	s_nop 0
	global_load_lds_dwordx4 v[242:243], off
	s_waitcnt lgkmcnt(0)
	v_mfma_f32_16x16x32_bf16 v[220:223], v[224:227], v[228:231], v[220:223]
	ds_read_b128 v[224:227], v184 offset:128
	ds_read_b128 v[228:231], v217
	v_add_u32_e32 v210, v151, v158
	global_load_dwordx4 v[20:23], v[244:245], off offset:0
	s_waitcnt lgkmcnt(0)
	v_mfma_f32_16x16x32_bf16 v[220:223], v[224:227], v[228:231], v[220:223]
	ds_read_b128 v[224:227], v184 offset:192
	ds_read_b128 v[228:231], v209
	v_add_u32_e32 v211, v151, v159
	global_load_dwordx4 v[16:19], v[244:245], off offset:64
	s_waitcnt lgkmcnt(0)
	v_mfma_f32_16x16x32_bf16 v[220:223], v[224:227], v[228:231], v[220:223]
	ds_read_b128 v[224:227], v184 offset:256
	ds_read_b128 v[228:231], v210
	v_pk_mul_f32 v[86:87], v[74:75], v[86:87]
	global_load_dwordx4 v[8:11], v[244:245], off offset:0x800
	s_waitcnt lgkmcnt(0)
	v_mfma_f32_16x16x32_bf16 v[220:223], v[224:227], v[228:231], v[220:223]
	ds_read_b128 v[224:227], v184 offset:320
	ds_read_b128 v[228:231], v211
	v_pk_mul_f32 v[84:85], v[72:73], v[84:85]
	global_load_dwordx4 v[4:7], v[244:245], off offset:0x840
	s_waitcnt lgkmcnt(0)
	v_mfma_f32_16x16x32_bf16 v[222:225], v[224:227], v[228:231], v[220:223]
	ds_read_b128 v[226:229], v184 offset:384
	s_nop 1
	v_add_u32_e32 v220, v151, v160
	ds_read_b128 v[230:233], v220
	global_load_dwordx4 v[24:27], v[250:251], off offset:0
	s_waitcnt lgkmcnt(0)
	v_mfma_f32_16x16x32_bf16 v[222:225], v[226:229], v[230:233], v[222:225]
	ds_read_b128 v[226:229], v184 offset:448
	v_add_u32_e32 v221, v151, v161
	ds_read_b128 v[230:233], v221
	v_pk_mul_f32 v[74:75], v[74:75], v[90:91]
	v_pk_mul_f32 v[72:73], v[72:73], v[88:89]
	v_mfma_f32_16x16x32_bf16 v[84:87], v[64:67], v[100:103], v[84:87]
	s_mov_b32 s47, s9
	v_mfma_f32_16x16x32_bf16 v[64:67], v[64:67], v[96:99], v[72:75]
	global_load_dwordx4 v[12:15], v[250:251], off offset:64
	s_waitcnt lgkmcnt(0)
	v_mfma_f32_16x16x32_bf16 v[222:225], v[226:229], v[230:233], v[222:225]
	v_mfma_f32_16x16x32_bf16 v[88:91], v[68:71], v[92:95], v[64:67]
	s_nop 4
	v_mul_f32_e64 v66, v62, v82
	v_mul_f32_e64 v67, v63, v83
	v_pk_mul_f32 v[64:65], v[60:61], v[80:81]
	v_pk_mul_f32 v[62:63], v[62:63], v[78:79]
	v_pk_mul_f32 v[60:61], v[60:61], v[76:77]
	v_mfma_f32_16x16x32_bf16 v[64:67], v[56:59], v[100:103], v[64:67]
	v_cvt_pk_bf16_f32 v222, v222, v223
	v_cvt_pk_bf16_f32 v223, v224, v225
	v_lshl_add_u64 v[224:225], v[144:145], 0, s[46:47]
	v_mfma_f32_16x16x32_bf16 v[56:59], v[56:59], v[96:99], v[60:63]
	v_lshlrev_b64 v[224:225], 6, v[224:225]
	v_lshl_add_u64 v[224:225], v[146:147], 0, v[224:225]
	global_store_dwordx2 v[224:225], v[222:223], off
	v_mfma_f32_16x16x32_bf16 v[84:87], v[68:71], v[104:107], v[84:87]
	s_waitcnt lgkmcnt(0)
	s_barrier
	v_mfma_f32_16x16x32_bf16 v[80:83], v[52:55], v[104:107], v[64:67]
	v_mfma_f32_16x16x32_bf16 v[76:79], v[52:55], v[92:95], v[56:59]
	s_nop 4
	v_cvt_pk_bf16_f32 v52, v84, v85
	v_cvt_pk_bf16_f32 v53, v86, v87
	ds_write_b64 v185, v[52:53]
	v_cvt_pk_bf16_f32 v52, v88, v89
	v_cvt_pk_bf16_f32 v53, v90, v91
	ds_write_b64 v185, v[52:53] offset:8448
	v_cvt_pk_bf16_f32 v52, v80, v81
	v_cvt_pk_bf16_f32 v53, v82, v83
	ds_write_b64 v186, v[52:53]
	v_cvt_pk_bf16_f32 v52, v76, v77
	v_cvt_pk_bf16_f32 v53, v78, v79
	ds_write_b64 v186, v[52:53] offset:8448
	s_waitcnt vmcnt(14) lgkmcnt(0)
	s_barrier
	s_add_i32 s87, s87, -3
	s_cmpk_gt_u32 s93, 0xf8
	s_mov_b32 s47, s93
	s_cbranch_scc1 .LBB0_376

.LBB0_374:
	s_or_b64 exec, exec, s[54:55]
	s_lshl_b64 s[54:55], s[52:53], 8
	v_lshl_add_u64 v[28:29], s[54:55], 0, v[114:115]
	v_lshlrev_b64 v[28:29], 7, v[28:29]
	v_lshl_add_u64 v[244:245], v[138:139], 0, v[28:29]
	s_lshl_b64 s[52:53], s[52:53], 10
	v_lshl_add_u64 v[250:251], v[140:141], 0, s[52:53]
	v_add_u32_e32 v199, v162, v117
	v_add_u32_e32 v200, v162, v119
	ds_read_b128 v[104:107], v199
	ds_read_b128 v[96:99], v200
	v_add_u32_e32 v201, v163, v117
	v_add_u32_e32 v202, v163, v119
	v_add_u32_e32 v203, v162, v113
	ds_read_b128 v[100:103], v201
	ds_read_b128 v[92:95], v202
	s_mov_b32 m0, s64
	s_nop 0
	global_load_lds_dwordx4 v[234:235], off
	s_mov_b32 m0, s73
	s_nop 0
	global_load_lds_dwordx4 v[236:237], off
	s_waitcnt lgkmcnt(0)
	v_cndmask_b32_e64 v211, v99, v107, s[42:43]
	v_cndmask_b32_e64 v210, v98, v106, s[42:43]
	v_cndmask_b32_e64 v209, v97, v105, s[42:43]
	v_cndmask_b32_e64 v208, v96, v104, s[42:43]
	ds_read_b128 v[212:215], v203 offset:36864
	v_add_u32_e32 v207, v163, v113
	ds_read_b128 v[216:219], v207 offset:36864
	s_mov_b32 m0, s74
	s_nop 0
	global_load_lds_dwordx4 v[238:239], off
	s_waitcnt lgkmcnt(0)
	v_mfma_f32_16x16x32_bf16 v[208:211], v[208:211], v[212:215], 0
	v_cndmask_b32_e64 v215, v95, v103, s[42:43]
	v_cndmask_b32_e64 v214, v94, v102, s[42:43]
	v_cndmask_b32_e64 v213, v93, v101, s[42:43]
	v_cndmask_b32_e64 v212, v92, v100, s[42:43]
	v_pk_mul_f32 v[86:87], v[26:27], v[86:87]
	v_pk_mul_f32 v[84:85], v[24:25], v[84:85]
	v_mfma_f32_16x16x32_bf16 v[208:211], v[212:215], v[216:219], v[208:211]
	ds_read_b128 v[212:215], v184
	ds_read_b128 v[216:219], v194 offset:45056
	v_pk_mul_f32 v[26:27], v[26:27], v[90:91]
	v_pk_mul_f32 v[24:25], v[24:25], v[88:89]
	s_mov_b32 m0, s75
	s_nop 0
	global_load_lds_dwordx4 v[240:241], off
	s_waitcnt lgkmcnt(0)
	v_mfma_f32_16x16x32_bf16 v[208:211], v[212:215], v[216:219], v[208:211]
	ds_read_b128 v[212:215], v184 offset:64
	ds_read_b128 v[216:219], v193 offset:45056
	s_add_i32 s8, s47, 4
	s_add_i32 s54, s87, 3
	s_mov_b32 m0, s78
	s_nop 0
	global_load_lds_dwordx4 v[242:243], off
	s_waitcnt lgkmcnt(0)
	v_mfma_f32_16x16x32_bf16 v[208:211], v[212:215], v[216:219], v[208:211]
	ds_read_b128 v[212:215], v184 offset:128
	ds_read_b128 v[216:219], v192 offset:45056
	s_and_b64 s[52:53], s[30:31], exec
	s_cselect_b32 s8, s8, s54
	global_load_dwordx4 v[44:47], v[244:245], off offset:0
	s_waitcnt lgkmcnt(0)
	v_mfma_f32_16x16x32_bf16 v[208:211], v[212:215], v[216:219], v[208:211]
	ds_read_b128 v[212:215], v184 offset:192
	ds_read_b128 v[216:219], v191 offset:45056
	s_lshl_b32 s8, s8, 6
	global_load_dwordx4 v[40:43], v[244:245], off offset:64
	s_waitcnt lgkmcnt(0)
	v_mfma_f32_16x16x32_bf16 v[208:211], v[212:215], v[216:219], v[208:211]
	ds_read_b128 v[212:215], v184 offset:256
	ds_read_b128 v[216:219], v188 offset:45056
	global_load_dwordx4 v[32:35], v[244:245], off offset:0x800
	s_waitcnt lgkmcnt(0)
	v_mfma_f32_16x16x32_bf16 v[208:211], v[212:215], v[216:219], v[208:211]
	ds_read_b128 v[212:215], v184 offset:320
	ds_read_b128 v[216:219], v187 offset:45056
	global_load_dwordx4 v[28:31], v[244:245], off offset:0x840
	s_waitcnt lgkmcnt(0)
	v_mfma_f32_16x16x32_bf16 v[208:211], v[212:215], v[216:219], v[208:211]
	ds_read_b128 v[212:215], v184 offset:384
	ds_read_b128 v[216:219], v189 offset:45056
	global_load_dwordx4 v[48:51], v[250:251], off offset:0
	s_waitcnt lgkmcnt(0)
	v_mfma_f32_16x16x32_bf16 v[208:211], v[212:215], v[216:219], v[208:211]
	ds_read_b128 v[212:215], v184 offset:448
	ds_read_b128 v[216:219], v190 offset:45056
	v_mfma_f32_16x16x32_bf16 v[84:87], v[20:23], v[104:107], v[84:87]
	v_mfma_f32_16x16x32_bf16 v[20:23], v[20:23], v[96:99], v[24:27]
	global_load_dwordx4 v[36:39], v[250:251], off offset:64
	s_waitcnt lgkmcnt(0)
	v_mfma_f32_16x16x32_bf16 v[208:211], v[212:215], v[216:219], v[208:211]
	v_mfma_f32_16x16x32_bf16 v[84:87], v[16:19], v[100:103], v[84:87]
	v_mfma_f32_16x16x32_bf16 v[88:91], v[16:19], v[92:95], v[20:23]
	v_mul_f32_e64 v18, v14, v82
	v_mul_f32_e64 v19, v15, v83
	v_pk_mul_f32 v[16:17], v[12:13], v[80:81]
	v_pk_mul_f32 v[14:15], v[14:15], v[78:79]
	v_pk_mul_f32 v[12:13], v[12:13], v[76:77]
	v_mfma_f32_16x16x32_bf16 v[16:19], v[8:11], v[104:107], v[16:19]
	v_cvt_pk_bf16_f32 v208, v208, v209
	v_cvt_pk_bf16_f32 v209, v210, v211
	v_lshl_add_u64 v[210:211], v[144:145], 0, s[8:9]
	v_mfma_f32_16x16x32_bf16 v[8:11], v[8:11], v[96:99], v[12:15]
	v_lshlrev_b64 v[210:211], 6, v[210:211]
	v_lshl_add_u64 v[210:211], v[146:147], 0, v[210:211]
	global_store_dwordx2 v[210:211], v[208:209], off
	v_mfma_f32_16x16x32_bf16 v[80:83], v[4:7], v[100:103], v[16:19]
	s_waitcnt lgkmcnt(0)
	s_barrier
	v_mfma_f32_16x16x32_bf16 v[76:79], v[4:7], v[92:95], v[8:11]
	v_cvt_pk_bf16_f32 v4, v84, v85
	v_cvt_pk_bf16_f32 v5, v86, v87
	ds_write_b64 v185, v[4:5]
	v_cvt_pk_bf16_f32 v4, v88, v89
	v_cvt_pk_bf16_f32 v5, v90, v91
	ds_write_b64 v185, v[4:5] offset:8448
	v_cvt_pk_bf16_f32 v4, v80, v81
	v_cvt_pk_bf16_f32 v5, v82, v83
	ds_write_b64 v186, v[4:5]
	v_cvt_pk_bf16_f32 v4, v76, v77
	v_cvt_pk_bf16_f32 v5, v78, v79
	ds_write_b64 v186, v[4:5] offset:8448
	s_waitcnt vmcnt(14) lgkmcnt(0)
	s_barrier
	s_add_i32 s8, s47, 7
	s_and_b64 s[52:53], s[30:31], exec
	s_cselect_b32 s8, s8, s87
	s_lshl_b32 s47, s8, 6
	s_add_i32 s52, s47, s71
	s_ashr_i32 s53, s52, 31
	s_lshl_b64 s[52:53], s[52:53], 11
	s_add_u32 s52, s83, s52
	s_addc_u32 s53, s86, s53
	v_lshl_add_u64 v[234:235], v[122:123], 1, s[52:53]
	v_lshl_add_u64 v[236:237], v[124:125], 1, s[52:53]
	v_lshl_add_u64 v[238:239], v[126:127], 1, s[52:53]
	v_lshl_add_u64 v[240:241], v[128:129], 1, s[52:53]
	s_add_i32 s52, s8, s68
	s_ashr_i32 s53, s52, 31
	s_lshl_b64 s[54:55], s[52:53], 13
	v_lshl_add_u64 v[242:243], v[136:137], 0, s[54:55]
	s_and_saveexec_b64 s[54:55], s[38:39]
	s_cbranch_execz .LBB0_369
	s_lshl_b64 s[94:95], s[52:53], 16
	s_add_i32 s8, s65, 0
	v_lshl_add_u64 v[4:5], v[142:143], 0, s[94:95]
	s_add_i32 m0, s8, 0x13000
	s_nop 0
	global_load_lds_dwordx4 v[4:5], off
	s_branch .LBB0_369
